# P3 select_row: one masked LDS-DMA dword load per 128-byte line warms L2 with the score row of ticket k+8 (same b, t-128) at each row start
# baseline (speedup 1.0000x reference)
; DI size_t sc_rowoff(int b, int t) { const int c = t >> 6; return (size_t)b * SC_PB + (size_t)4096 * (c * (c + 1) / 2) + (size_t)(t & 63) * (64 * (c + 1)); }
; DI void select_row(const float* SC, unsigned* dmask, int b, int t, int lane) {
;     unsigned* dm = dmask + ((size_t)b * SEQ + t) * 64;
;     const int nvalid = t + 1;
;     if (nvalid <= 256) {
;         const int w = lane;
;         const int lo = 32 * w; unsigned bits = 0u;
;         if (lo + 31 <= t) bits = 0xffffffffu; else if (lo <= t) bits = (2u << (t - lo)) - 1u;
;         dm[w] = bits; return;
;     }
;     const int nch = (nvalid + 255) >> 8;
;     const float* srow = SC + sc_rowoff(b, t) + 4 * lane;
;     unsigned u[8][4];
; #pragma unroll
;     for (int k = 0; k < 8; ++k) {
;         if (k < nch) {
;             const f32x4 v = *(const f32x4*)(srow + 256 * k);
; #pragma unroll
;             for (int e = 0; e < 4; ++e) { const unsigned bits = __builtin_bit_cast(unsigned, v[e] + 0.0f); const unsigned key = ((int)bits < 0) ? ~bits : (bits | 0x80000000u);
;                 u[k][e] = (256 * k + 4 * lane + e <= t) ? key : 0u; }
;         } else { u[k][0] = 0u; u[k][1] = 0u; u[k][2] = 0u; u[k][3] = 0u; }
;     }
.Lsel_pf_done:
	s_mov_b32 s99, 0x80000000
	v_mov_b32_e32 v121, v43
	v_lshl_add_u64 v[10:11], s[8:9], 0, v[120:121]
	s_cmpk_lt_u32 s65, 0x180
	s_cbranch_scc1 .Lsel_l2pf_skip
	s_add_i32 s8, s65, 0xffffff80
	s_lshr_b32 s9, s8, 6
	s_add_i32 s10, s9, 1
	s_mul_i32 s9, s9, s10
	s_lshl_b32 s9, s9, 13
	s_and_b32 s8, s8, 63
	s_mul_i32 s8, s8, s10
	s_lshl_b32 s8, s8, 8
	s_add_i32 s8, s8, s9
	s_and_b32 s14, s92, 8
	s_and_b32 s98, s47, 7
	s_or_b32 s14, s14, s98
	s_mul_i32 s14, s14, 0x840000
	s_add_i32 s8, s8, s14
	s_add_u32 s8, s44, s8
	s_addc_u32 s9, s45, 0
	s_lshl_b32 s10, s10, 1
	s_lshl_b64 s[10:11], 1, s10
	s_add_u32 s10, s10, -1
	s_addc_u32 s11, s11, -1
	v_lshlrev_b32_e32 v189, 3, v120
	s_mov_b32 m0, 0x1000
	s_mov_b64 vcc, exec
	s_mov_b64 exec, s[10:11]
	s_nop 1
	global_load_lds_dword v189, s[8:9]
	s_mov_b64 exec, vcc
.Lsel_l2pf_skip:
	s_cmpk_gt_u32 s65, 0x1ff
	v_mov_b32_e32 v28, 0
	s_cselect_b64 s[10:11], -1, 0
	s_cmpk_lt_u32 s65, 0x200
	v_mov_b32_e32 v32, 0
	v_mov_b32_e32 v42, 0
	v_mov_b32_e32 v33, 0
	v_mov_b32_e32 v41, 0
	s_cbranch_scc1 .LBB0_539
	s_waitcnt vmcnt(0)
	v_pk_add_f32 v[150:151], v[150:151], 0 op_sel_hi:[1,0]
	v_pk_add_f32 v[152:153], v[152:153], 0 op_sel_hi:[1,0]
	v_ashrrev_i32_e32 v146, 31, v150
	v_ashrrev_i32_e32 v147, 31, v151
	v_ashrrev_i32_e32 v148, 31, v152
	v_ashrrev_i32_e32 v149, 31, v153
	v_bitop3_b32 v33, v150, v146, s99 bitop3:0x1e
	v_bitop3_b32 v41, v151, v147, s99 bitop3:0x1e
	v_bitop3_b32 v32, v152, v148, s99 bitop3:0x1e
	v_bitop3_b32 v42, v153, v149, s99 bitop3:0x1e
	s_cmpk_gt_u32 s65, 0x2fe
	s_cbranch_scc1 .Lsel_cv_2
	v_cmp_ge_u32_e32 vcc, s65, v86
	s_nop 1
	v_cndmask_b32_e32 v33, 0, v33, vcc
	v_cmp_ge_u32_e32 vcc, s65, v87
	s_nop 1
	v_cndmask_b32_e32 v41, 0, v41, vcc
	v_or_b32_e32 v12, 0x202, v88
	v_cmp_ge_u32_e32 vcc, s65, v12
	s_nop 1
	v_cndmask_b32_e32 v32, 0, v32, vcc
	v_cmp_ge_u32_e32 vcc, s65, v89
	s_nop 1
	v_cndmask_b32_e32 v42, 0, v42, vcc
